# attention A and B loops: K/V LDS staging stores moved into the P.V MFMA shadow (as for D)
# baseline (speedup 1.0000x reference)
; #define AP_GLOAD_K(j, t) do { const char* kt_ = (const char*)Kb + (size_t)AP_CL(t) * 64 * kpitch * 2; \
;     _Pragma("unroll") for (int i_ = 0; i_ < KPT; ++i_) { if (i_ + 1 < KPT || kact1) kreg[j][i_] = *(const u32x4*)(kt_ + kgo[i_]); } } while (0)
; #define AP_GLOAD_V(j, t) do { const char* vt_ = (const char*)Vb + (size_t)AP_CL(t) * 64 * vpitch * 2; \
;     _Pragma("unroll") for (int i_ = 0; i_ < VPT; ++i_) vreg[j][i_] = *(const u32x4*)(vt_ + vgo[i_]); } while (0)
; template <int KW, int DQK, int DV>
; DI void attn_dense_pair(LAS unsigned char* lds, const int tid, const bf16_t* Qw, int qpitch, const bf16_t* Kb, int kpitch, const bf16_t* Vb, int vpitch,
;                         float nbound, f32x16 (&o)[DV / 32], float& l_out) {
;     ...
;     for (int t = 1; t + 1 < NT; t += 2) {
;         AP_GLOAD_K(0, t + 2); AP_GLOAD_K(1, t + 3); AP_GLOAD_V(0, t + 1); AP_GLOAD_V(1, t + 2);
;         f32x16 pn0, pn1;
;         __builtin_amdgcn_sched_barrier(0);
;         tile_step<DQK, KP, DV, VP, true, 4, true>(pw, pn0, pn1, cvec, ls, o, qf, lds + (t & 3) * KT + koff, lds + ((t - 1) & 3) * VT + voff, &osum, onesf);
;         __builtin_amdgcn_sched_barrier(0);
;         tile_step<DQK, KP, DV, VP, true, 4, true>(pw, pn0, pn1, cvec, ls, o, qf, lds + ((t + 1) & 3) * KT + koff, lds + (t & 3) * VT + voff, &osum, onesf);
.LBB0_383:
	s_add_i32 s9, s34, 1
	s_add_i32 s8, s34, 2
	s_add_i32 s29, s34, -1
	s_add_i32 s14, s6, 0x8000
	s_cmpk_lt_u32 s34, 0x7d
	s_cselect_b64 s[0:1], -1, 0
	s_and_b64 vcc, s[0:1], exec
	v_lshl_add_u64 v[80:81], v[178:179], 0, s[6:7]
	s_cselect_b32 s14, s14, 0xfe000
	v_lshl_add_u64 v[82:83], v[176:177], 0, s[14:15]
	global_load_dwordx4 v[162:165], v[80:81], off
	global_load_dwordx4 v[150:153], v[82:83], off
	v_add_co_u32_e64 v80, s[0:1], s70, v180
	s_nop 1
	v_addc_co_u32_e64 v81, s[0:1], 0, v181, s[0:1]
	global_load_dwordx4 v[154:157], v[180:181], off
	global_load_dwordx4 v[158:161], v[80:81], off
	s_and_b32 s1, s34, 3
	s_mul_i32 s0, s1, 0x2400
	v_add_u32_e32 v175, s0, v183
	ds_read_b128 v[80:83], v175
	ds_read_b128 v[194:197], v175 offset:32
	ds_read_b128 v[198:201], v175 offset:4608
	ds_read_b128 v[202:205], v175 offset:4640
	s_and_b32 s0, s29, 3
	s_mul_i32 s14, s0, 0x3000
	v_add_u32_e32 v186, s14, v185
	ds_read_b128 v[206:209], v175 offset:64
	ds_read_b64_tr_b16 v[222:223], v186 offset:36864
	ds_read_b64_tr_b16 v[224:225], v186 offset:38400
	s_waitcnt lgkmcnt(6)
	v_mfma_f32_32x32x16_bf16 v[96:111], v[80:83], v[130:133], v[64:79]
	s_waitcnt lgkmcnt(4)
	v_mfma_f32_32x32x16_bf16 v[80:95], v[198:201], v[130:133], v[64:79]
	ds_read_b128 v[198:201], v175 offset:4672
	ds_read_b64_tr_b16 v[226:227], v186 offset:36928
	ds_read_b64_tr_b16 v[228:229], v186 offset:38464
	v_mfma_f32_32x32x16_bf16 v[48:63], v[112:115], v[146:149], v[48:63]
	v_mfma_f32_32x32x16_bf16 v[96:111], v[194:197], v[124:127], v[96:111]
	ds_read_b128 v[194:197], v175 offset:96
	ds_read_b64_tr_b16 v[230:231], v186 offset:39936
	ds_read_b64_tr_b16 v[232:233], v186 offset:41472
	s_waitcnt lgkmcnt(9)
	v_mfma_f32_32x32x16_bf16 v[80:95], v[202:205], v[124:127], v[80:95]
	ds_read_b128 v[202:205], v175 offset:4704
	ds_read_b64_tr_b16 v[234:235], v186 offset:40000
	ds_read_b64_tr_b16 v[236:237], v186 offset:41536
	v_mfma_f32_32x32x16_bf16 v[48:63], v[112:115], v[142:145], v[48:63]
	s_waitcnt lgkmcnt(11)
	v_mfma_f32_32x32x16_bf16 v[96:111], v[206:209], v[120:123], v[96:111]
	ds_read_b64_tr_b16 v[206:207], v186 offset:43008
	ds_read_b64_tr_b16 v[208:209], v186 offset:44544
	s_waitcnt lgkmcnt(10)
	v_mfma_f32_32x32x16_bf16 v[80:95], v[198:201], v[120:123], v[80:95]
	ds_read_b64_tr_b16 v[198:199], v186 offset:43072
	ds_read_b64_tr_b16 v[200:201], v186 offset:44608
	v_mfma_f32_32x32x16_bf16 v[48:63], v[112:115], v[138:141], v[48:63]
	s_waitcnt lgkmcnt(9)
	v_mfma_f32_32x32x16_bf16 v[96:111], v[194:197], v[116:119], v[96:111]
	ds_read_b64_tr_b16 v[194:195], v186 offset:46080
	ds_read_b64_tr_b16 v[196:197], v186 offset:47616
	s_waitcnt lgkmcnt(8)
	v_mfma_f32_32x32x16_bf16 v[80:95], v[202:205], v[116:119], v[80:95]
	ds_read_b64_tr_b16 v[202:203], v186 offset:46144
	ds_read_b64_tr_b16 v[204:205], v186 offset:47680
	v_mfma_f32_32x32x16_bf16 v[48:63], v[112:115], v[134:137], v[48:63]
	v_mfma_f32_32x32x16_bf16 v[32:47], v[222:225], v[146:149], v[32:47]
	s_nop 3
	v_exp_f32_e32 v96, v96
	v_exp_f32_e32 v97, v97
	v_exp_f32_e32 v98, v98
	v_exp_f32_e32 v99, v99
	v_mfma_f32_32x32x16_bf16 v[16:31], v[226:229], v[146:149], v[16:31]
	v_exp_f32_e32 v100, v100
	v_exp_f32_e32 v101, v101
	v_exp_f32_e32 v102, v102
	v_exp_f32_e32 v103, v103
	v_mfma_f32_32x32x16_bf16 v[32:47], v[230:233], v[142:145], v[32:47]
	v_exp_f32_e32 v104, v104
	v_exp_f32_e32 v105, v105
	v_exp_f32_e32 v106, v106
	v_exp_f32_e32 v107, v107
	s_waitcnt lgkmcnt(8)
	v_mfma_f32_32x32x16_bf16 v[16:31], v[234:237], v[142:145], v[16:31]
	v_exp_f32_e32 v108, v108
	v_exp_f32_e32 v109, v109
	v_exp_f32_e32 v110, v110
	v_exp_f32_e32 v111, v111
	s_waitcnt lgkmcnt(6)
	v_mfma_f32_32x32x16_bf16 v[32:47], v[206:209], v[138:141], v[32:47]
	v_exp_f32_e32 v80, v80
	v_exp_f32_e32 v81, v81
	v_exp_f32_e32 v82, v82
	v_exp_f32_e32 v83, v83
	s_waitcnt lgkmcnt(4)
	v_mfma_f32_32x32x16_bf16 v[16:31], v[198:201], v[138:141], v[16:31]
	v_exp_f32_e32 v84, v84
	v_exp_f32_e32 v85, v85
	v_exp_f32_e32 v86, v86
	v_exp_f32_e32 v87, v87
	s_waitcnt lgkmcnt(2)
	v_mfma_f32_32x32x16_bf16 v[32:47], v[194:197], v[134:137], v[32:47]
	v_exp_f32_e32 v88, v88
	v_exp_f32_e32 v89, v89
	v_exp_f32_e32 v90, v90
	v_exp_f32_e32 v91, v91
	s_waitcnt lgkmcnt(0)
	v_mfma_f32_32x32x16_bf16 v[16:31], v[202:205], v[134:137], v[16:31]
	v_cvt_pk_bf16_f32 v135, v90, v91
	v_cvt_pk_bf16_f32 v134, v88, v89
	v_cvt_pk_bf16_f32 v141, v86, v87
	v_cvt_pk_bf16_f32 v140, v84, v85
	v_cvt_pk_bf16_f32 v139, v82, v83
	v_cvt_pk_bf16_f32 v138, v80, v81
	v_cvt_pk_bf16_f32 v145, v110, v111
	v_cvt_pk_bf16_f32 v144, v108, v109
	v_cvt_pk_bf16_f32 v143, v106, v107
	v_cvt_pk_bf16_f32 v142, v104, v105
	v_cvt_pk_bf16_f32 v149, v102, v103
	v_cvt_pk_bf16_f32 v148, v100, v101
	v_cvt_pk_bf16_f32 v147, v98, v99
	v_cvt_pk_bf16_f32 v146, v96, v97
	v_exp_f32_e32 v92, v92
	v_exp_f32_e32 v93, v93
	v_exp_f32_e32 v94, v94
	v_exp_f32_e32 v95, v95
	v_cvt_pk_bf16_f32 v136, v92, v93
	v_cvt_pk_bf16_f32 v137, v94, v95
	s_and_b32 s9, s9, 3
	s_mul_i32 s14, s9, 0x2400
	v_add_u32_e32 v175, s14, v183
	ds_read_b128 v[80:83], v175
	ds_read_b128 v[194:197], v175 offset:32
	ds_read_b128 v[198:201], v175 offset:4608
	ds_read_b128 v[202:205], v175 offset:4640
	s_mulk_i32 s1, 0x3000
	v_add_u32_e32 v186, s1, v185
	ds_read_b128 v[206:209], v175 offset:64
	ds_read_b64_tr_b16 v[222:223], v186 offset:36864
	ds_read_b64_tr_b16 v[224:225], v186 offset:38400
	s_waitcnt lgkmcnt(6)
	v_mfma_f32_32x32x16_bf16 v[96:111], v[80:83], v[130:133], v[64:79]
	s_waitcnt lgkmcnt(4)
; #define AP_LSTORE_K(j, t) do { \
;     _Pragma("unroll") for (int i_ = 0; i_ < KPT; ++i_) { if (i_ + 1 < KPT || kact1) *(LAS u32x4*)(lds + ((t) & 3) * KT + klo[i_]) = kreg[j][i_]; } } while (0)
; #define AP_LSTORE_V(j, t) do { \
;     _Pragma("unroll") for (int i_ = 0; i_ < VPT; ++i_) *(LAS u32x4*)(lds + ((t) & 3) * VT + vlo[i_]) = vreg[j][i_]; } while (0)
; template <int KW, int DQK, int DV>
; DI void attn_dense_pair(LAS unsigned char* lds, const int tid, const bf16_t* Qw, int qpitch, const bf16_t* Kb, int kpitch, const bf16_t* Vb, int vpitch,
;                         float nbound, f32x16 (&o)[DV / 32], float& l_out) {
;     ...
;         tile_step<DQK, KP, DV, VP, true, 4, true>(pw, pn0, pn1, cvec, ls, o, qf, lds + ((t + 1) & 3) * KT + koff, lds + (t & 3) * VT + voff, &osum, onesf);
;         AP_LSTORE_K(0, t + 2); AP_LSTORE_K(1, t + 3); AP_LSTORE_V(0, t + 1); AP_LSTORE_V(1, t + 2);
;         __syncthreads();
	v_mfma_f32_32x32x16_bf16 v[80:95], v[198:201], v[130:133], v[64:79]
	ds_read_b128 v[198:201], v175 offset:4672
	ds_read_b64_tr_b16 v[226:227], v186 offset:36928
	ds_read_b64_tr_b16 v[228:229], v186 offset:38464
	v_mfma_f32_32x32x16_bf16 v[48:63], v[112:115], v[146:149], v[48:63]
	v_mfma_f32_32x32x16_bf16 v[96:111], v[194:197], v[124:127], v[96:111]
	ds_read_b128 v[194:197], v175 offset:96
	ds_read_b64_tr_b16 v[230:231], v186 offset:39936
	ds_read_b64_tr_b16 v[232:233], v186 offset:41472
	s_waitcnt lgkmcnt(9)
	v_mfma_f32_32x32x16_bf16 v[80:95], v[202:205], v[124:127], v[80:95]
	ds_read_b128 v[202:205], v175 offset:4704
	ds_read_b64_tr_b16 v[234:235], v186 offset:40000
	ds_read_b64_tr_b16 v[236:237], v186 offset:41536
	v_mfma_f32_32x32x16_bf16 v[48:63], v[112:115], v[142:145], v[48:63]
	s_waitcnt lgkmcnt(11)
	v_mfma_f32_32x32x16_bf16 v[96:111], v[206:209], v[120:123], v[96:111]
	ds_read_b64_tr_b16 v[206:207], v186 offset:43008
	ds_read_b64_tr_b16 v[208:209], v186 offset:44544
	s_waitcnt lgkmcnt(10)
	v_mfma_f32_32x32x16_bf16 v[80:95], v[198:201], v[120:123], v[80:95]
	ds_read_b64_tr_b16 v[198:199], v186 offset:43072
	ds_read_b64_tr_b16 v[200:201], v186 offset:44608
	v_mfma_f32_32x32x16_bf16 v[48:63], v[112:115], v[138:141], v[48:63]
	s_waitcnt lgkmcnt(9)
	v_mfma_f32_32x32x16_bf16 v[96:111], v[194:197], v[116:119], v[96:111]
	ds_read_b64_tr_b16 v[194:195], v186 offset:46080
	ds_read_b64_tr_b16 v[196:197], v186 offset:47616
	s_waitcnt lgkmcnt(8)
	v_mfma_f32_32x32x16_bf16 v[80:95], v[202:205], v[116:119], v[80:95]
	ds_read_b64_tr_b16 v[202:203], v186 offset:46144
	ds_read_b64_tr_b16 v[204:205], v186 offset:47680
	s_and_b32 s1, s8, 3
	s_mul_i32 s14, s1, 0x2400
	v_add_u32_e32 v186, s14, v182
	s_mulk_i32 s0, 0x2400
	s_waitcnt vmcnt(3)
	ds_write_b128 v186, v[162:165]
	v_add_u32_e32 v186, s0, v182
	s_mulk_i32 s9, 0x3000
	s_waitcnt vmcnt(2)
	ds_write_b128 v186, v[150:153]
	v_add_u32_e32 v186, s9, v184
	s_mulk_i32 s1, 0x3000
	s_waitcnt vmcnt(1)
	ds_write_b128 v186, v[154:157] offset:36864
	v_add_u32_e32 v186, s1, v184
	s_waitcnt vmcnt(0)
	ds_write_b128 v186, v[158:161] offset:36864
	v_mfma_f32_32x32x16_bf16 v[48:63], v[112:115], v[134:137], v[48:63]
	v_mfma_f32_32x32x16_bf16 v[32:47], v[222:225], v[146:149], v[32:47]
	s_nop 3
	v_exp_f32_e32 v96, v96
	v_exp_f32_e32 v97, v97
	v_exp_f32_e32 v98, v98
	v_exp_f32_e32 v99, v99
	v_mfma_f32_32x32x16_bf16 v[16:31], v[226:229], v[146:149], v[16:31]
	v_exp_f32_e32 v100, v100
	v_exp_f32_e32 v101, v101
	v_exp_f32_e32 v102, v102
	v_exp_f32_e32 v103, v103
	v_mfma_f32_32x32x16_bf16 v[32:47], v[230:233], v[142:145], v[32:47]
	v_exp_f32_e32 v104, v104
	v_exp_f32_e32 v105, v105
	v_exp_f32_e32 v106, v106
	v_exp_f32_e32 v107, v107
	s_waitcnt lgkmcnt(12)
	v_mfma_f32_32x32x16_bf16 v[16:31], v[234:237], v[142:145], v[16:31]
	v_exp_f32_e32 v108, v108
	v_exp_f32_e32 v109, v109
	v_exp_f32_e32 v110, v110
	v_exp_f32_e32 v111, v111
	s_waitcnt lgkmcnt(10)
	v_mfma_f32_32x32x16_bf16 v[32:47], v[206:209], v[138:141], v[32:47]
	v_exp_f32_e32 v80, v80
	v_exp_f32_e32 v81, v81
	v_exp_f32_e32 v82, v82
	v_exp_f32_e32 v83, v83
	s_waitcnt lgkmcnt(8)
	v_mfma_f32_32x32x16_bf16 v[16:31], v[198:201], v[138:141], v[16:31]
	v_exp_f32_e32 v84, v84
	v_exp_f32_e32 v85, v85
	v_exp_f32_e32 v86, v86
	v_exp_f32_e32 v87, v87
	s_waitcnt lgkmcnt(6)
	v_mfma_f32_32x32x16_bf16 v[32:47], v[194:197], v[134:137], v[32:47]
	v_exp_f32_e32 v88, v88
	v_exp_f32_e32 v89, v89
	v_exp_f32_e32 v90, v90
	v_exp_f32_e32 v91, v91
	s_waitcnt lgkmcnt(4)
	v_mfma_f32_32x32x16_bf16 v[16:31], v[202:205], v[134:137], v[16:31]
	v_cvt_pk_bf16_f32 v135, v90, v91
	v_cvt_pk_bf16_f32 v134, v88, v89
	v_cvt_pk_bf16_f32 v141, v86, v87
	v_cvt_pk_bf16_f32 v140, v84, v85
	v_cvt_pk_bf16_f32 v139, v82, v83
	v_cvt_pk_bf16_f32 v138, v80, v81
	v_cvt_pk_bf16_f32 v145, v110, v111
	v_cvt_pk_bf16_f32 v144, v108, v109
	v_cvt_pk_bf16_f32 v143, v106, v107
	v_cvt_pk_bf16_f32 v142, v104, v105
	v_cvt_pk_bf16_f32 v149, v102, v103
	v_cvt_pk_bf16_f32 v148, v100, v101
	v_cvt_pk_bf16_f32 v147, v98, v99
	v_cvt_pk_bf16_f32 v146, v96, v97
	v_exp_f32_e32 v92, v92
	v_exp_f32_e32 v93, v93
	v_exp_f32_e32 v94, v94
	v_exp_f32_e32 v95, v95
	s_mov_b64 s[0:1], 0x460000
	s_add_u32 s6, s6, 0x4000
	v_cvt_pk_bf16_f32 v136, v92, v93
	v_cvt_pk_bf16_f32 v137, v94, v95
	v_lshl_add_u64 v[180:181], v[180:181], 0, s[0:1]
	s_addc_u32 s7, s7, 0
	s_mov_b32 s34, s8
	s_waitcnt lgkmcnt(0)
	s_barrier
	s_cbranch_vccnz .LBB0_383
; template <int KW, int DQK, int DV>
; DI void attn_dense_pair(LAS unsigned char* lds, const int tid, const bf16_t* Qw, int qpitch, const bf16_t* Kb, int kpitch, const bf16_t* Vb, int vpitch,
;                         float nbound, f32x16 (&o)[DV / 32], float& l_out) {
;     ...
;     { f32x16 pn0, pn1;
;       tile_step<DQK, KP, DV, VP, true, 4, true>(pw, pn0, pn1, cvec, ls, o, qf, lds + ((NT - 1) & 3) * KT + koff, lds + ((NT - 2) & 3) * VT + voff, &osum, onesf); }
;     rowsum_pw(pw, ls);
;     pv_tile<DV, VP>(o, pw, lds + ((NT - 1) & 3) * VT + voff);
	ds_read_b128 v[96:99], v183 offset:27648
	ds_read_b128 v[100:103], v183 offset:27680
	ds_read_b128 v[104:107], v183 offset:32256
	ds_read_b128 v[108:111], v183 offset:32288
	s_waitcnt lgkmcnt(3)
	v_mfma_f32_32x32x16_bf16 v[80:95], v[96:99], v[130:133], v[64:79]
	ds_read_b128 v[96:99], v183 offset:27712
	ds_read_b64_tr_b16 v[150:151], v185 offset:61440
	ds_read_b64_tr_b16 v[152:153], v185 offset:62976
	s_waitcnt lgkmcnt(4)
	v_mfma_f32_32x32x16_bf16 v[64:79], v[104:107], v[130:133], v[64:79]
	ds_read_b128 v[104:107], v183 offset:32320
	ds_read_b64_tr_b16 v[130:131], v185 offset:61504
	ds_read_b64_tr_b16 v[132:133], v185 offset:63040
	v_mfma_f32_32x32x16_bf16 v[48:63], v[112:115], v[146:149], v[48:63]
	v_mfma_f32_32x32x16_bf16 v[80:95], v[100:103], v[124:127], v[80:95]
	ds_read_b128 v[100:103], v183 offset:27744
	ds_read_b64_tr_b16 v[154:155], v185 offset:64512
	ds_read_b64_tr_b16 v[156:157], v190 offset:4608
	s_waitcnt lgkmcnt(9)
	v_mfma_f32_32x32x16_bf16 v[64:79], v[108:111], v[124:127], v[64:79]
	ds_read_b128 v[108:111], v183 offset:32352
	ds_read_b64_tr_b16 v[124:125], v185 offset:64576
	ds_read_b64_tr_b16 v[126:127], v190 offset:4672
	v_mfma_f32_32x32x16_bf16 v[48:63], v[112:115], v[142:145], v[48:63]
	s_waitcnt lgkmcnt(11)
	v_mfma_f32_32x32x16_bf16 v[80:95], v[96:99], v[120:123], v[80:95]
	ds_read_b64_tr_b16 v[96:97], v190 offset:6144
	ds_read_b64_tr_b16 v[98:99], v190 offset:7680
	s_waitcnt lgkmcnt(10)
	v_mfma_f32_32x32x16_bf16 v[64:79], v[104:107], v[120:123], v[64:79]
	ds_read_b64_tr_b16 v[104:105], v190 offset:6208
	ds_read_b64_tr_b16 v[106:107], v190 offset:7744
	v_mfma_f32_32x32x16_bf16 v[48:63], v[112:115], v[138:141], v[48:63]
	s_waitcnt lgkmcnt(9)
	v_mfma_f32_32x32x16_bf16 v[80:95], v[100:103], v[116:119], v[80:95]
	ds_read_b64_tr_b16 v[100:101], v190 offset:9216
	ds_read_b64_tr_b16 v[102:103], v190 offset:10752
	s_waitcnt lgkmcnt(8)
	v_mfma_f32_32x32x16_bf16 v[64:79], v[108:111], v[116:119], v[64:79]
	ds_read_b64_tr_b16 v[108:109], v190 offset:9280
	ds_read_b64_tr_b16 v[110:111], v190 offset:10816
	v_mfma_f32_32x32x16_bf16 v[48:63], v[112:115], v[134:137], v[48:63]
	v_mfma_f32_32x32x16_bf16 v[32:47], v[150:153], v[146:149], v[32:47]
	s_nop 10
	v_exp_f32_e32 v49, v80
	v_exp_f32_e32 v52, v81
	v_exp_f32_e32 v53, v82
	v_exp_f32_e32 v62, v83
	v_mfma_f32_32x32x16_bf16 v[16:31], v[130:133], v[146:149], v[16:31]
	v_exp_f32_e32 v63, v84
	v_exp_f32_e32 v80, v85
	v_exp_f32_e32 v81, v86
	v_exp_f32_e32 v82, v87
	v_mfma_f32_32x32x16_bf16 v[32:47], v[154:157], v[142:145], v[32:47]
	v_exp_f32_e32 v58, v88
	v_exp_f32_e32 v83, v89
	v_exp_f32_e32 v59, v90
	v_exp_f32_e32 v84, v91
	s_waitcnt lgkmcnt(8)
	v_mfma_f32_32x32x16_bf16 v[16:31], v[124:127], v[142:145], v[16:31]
	v_exp_f32_e32 v60, v92
	v_exp_f32_e32 v85, v93
	v_exp_f32_e32 v61, v94
	v_exp_f32_e32 v86, v95
	s_waitcnt lgkmcnt(6)
	v_mfma_f32_32x32x16_bf16 v[32:47], v[96:99], v[138:141], v[32:47]
	v_exp_f32_e32 v54, v64
	v_exp_f32_e32 v64, v65
	v_exp_f32_e32 v55, v66
	v_exp_f32_e32 v65, v67
	s_waitcnt lgkmcnt(4)
	v_mfma_f32_32x32x16_bf16 v[16:31], v[104:107], v[138:141], v[16:31]
	v_exp_f32_e32 v56, v68
	v_exp_f32_e32 v66, v69
	v_exp_f32_e32 v57, v70
	v_exp_f32_e32 v67, v71
	s_waitcnt lgkmcnt(2)
	v_mfma_f32_32x32x16_bf16 v[32:47], v[100:103], v[134:137], v[32:47]
	v_exp_f32_e32 v50, v72
	v_exp_f32_e32 v68, v73
	v_exp_f32_e32 v51, v74
	v_exp_f32_e32 v69, v75
	s_waitcnt lgkmcnt(0)
	v_mfma_f32_32x32x16_bf16 v[16:31], v[108:111], v[134:137], v[16:31]
	v_exp_f32_e32 v101, v76
	v_exp_f32_e32 v106, v77
	v_exp_f32_e32 v107, v78
	v_exp_f32_e32 v108, v79
	v_cvt_pk_bf16_f32 v51, v51, v69
	v_cvt_pk_bf16_f32 v50, v50, v68
	v_cvt_pk_bf16_f32 v57, v57, v67
	v_cvt_pk_bf16_f32 v56, v56, v66
	v_cvt_pk_bf16_f32 v55, v55, v65
	v_cvt_pk_bf16_f32 v54, v54, v64
	v_cvt_pk_bf16_f32 v61, v61, v86
	v_cvt_pk_bf16_f32 v60, v60, v85
	v_cvt_pk_bf16_f32 v59, v59, v84
	v_cvt_pk_bf16_f32 v58, v58, v83
	v_cvt_pk_bf16_f32 v69, v81, v82
	v_cvt_pk_bf16_f32 v68, v63, v80
	v_cvt_pk_bf16_f32 v67, v53, v62
	v_cvt_pk_bf16_f32 v66, v49, v52
	v_mov_b32_e32 v49, v252
	s_mov_b32 s0, s20
	ds_read_b64_tr_b16 v[76:77], v193 offset:36864
	ds_read_b64_tr_b16 v[78:79], v193 offset:38400
	ds_read_b64_tr_b16 v[82:83], v193 offset:38464
	ds_read_b64_tr_b16 v[80:81], v193 offset:36928
	ds_read_b64_tr_b16 v[84:85], v193 offset:39936
	ds_read_b64_tr_b16 v[86:87], v193 offset:41472
	ds_read_b64_tr_b16 v[90:91], v193 offset:41536
	ds_read_b64_tr_b16 v[88:89], v193 offset:40000
	ds_read_b64_tr_b16 v[92:93], v193 offset:43008
	ds_read_b64_tr_b16 v[94:95], v193 offset:44544
	ds_read_b64_tr_b16 v[72:73], v193 offset:44608
	ds_read_b64_tr_b16 v[70:71], v193 offset:43072
	ds_read_b64_tr_b16 v[96:97], v193 offset:46080
	ds_read_b64_tr_b16 v[98:99], v193 offset:47616
	ds_read_b64_tr_b16 v[64:65], v193 offset:47680
	ds_read_b64_tr_b16 v[62:63], v193 offset:46144
	s_waitcnt lgkmcnt(0)
	s_barrier
; DI float bflo(unsigned u) { return __uint_as_float(u << 16); }
; DI float bfhi(unsigned u) { return __uint_as_float(u & 0xffff0000u); }
; DI float shx(float v, int m, int lane) { return __int_as_float(__builtin_amdgcn_ds_bpermute((lane ^ m) << 2, __float_as_int(v))); }
; template <int KW, int DQK, int DV>
; DI void attn_dense_pair(LAS unsigned char* lds, const int tid, const bf16_t* Qw, int qpitch, const bf16_t* Kb, int kpitch, const bf16_t* Vb, int vpitch,
;                         float nbound, f32x16 (&o)[DV / 32], float& l_out) {
;     ...
;     rowsum_pw(pw, ls);
;     pv_tile<DV, VP>(o, pw, lds + ((NT - 1) & 3) * VT + voff);
;     float l = (ls[0] + ls[1]) + (ls[2] + ls[3]);
;     __syncthreads();
;     ...
;     l += shx(l, 32, lane);
;     l += __int_as_float(__builtin_amdgcn_ds_bpermute((lane & 31) << 2, __float_as_int(osum[0])));
;     l_out = l;
; DI void store_y64(const f32x16 (&o)[2], float linv, bf16_t* Y, const bf16_t* proj, int token, int ycol, int hi) {
; #pragma unroll
;     for (int d0 = 0; d0 < 2; ++d0)
; #pragma unroll
;         for (int g = 0; g < 4; ++g) {
;             const int col = ycol + 32 * d0 + 8 * g + 4 * hi;
;             const u32x2 gv = *(const u32x2*)(proj + (size_t)token * LDP + C_SILU + col);
;             u32x2 w;
;             w.x = cvt_pk(o[d0][4 * g + 0] * linv * bflo(gv.x), o[d0][4 * g + 1] * linv * bfhi(gv.x));
;             w.y = cvt_pk(o[d0][4 * g + 2] * linv * bflo(gv.y), o[d0][4 * g + 3] * linv * bfhi(gv.y));
;             *(u32x2*)(Y + (size_t)token * DM + col) = w;
;         }
	s_lshl_b32 s1, s0, 8
	s_and_b32 s1, s1, 0x1f00
	s_add_i32 s1, s1, s21
	v_and_or_b32 v100, v49, 31, s1
	s_lshl_b32 s0, s0, 1
	v_ashrrev_i32_e32 v49, 3, v49
	s_andn2_b32 s0, s0, 63
	v_and_b32_e32 v49, -4, v49
	v_add_u32_e32 v49, s0, v49
	v_add_u32_e32 v52, 0x200, v49
	v_mov_b64_e32 v[74:75], s[2:3]
	v_mad_i64_i32 v[74:75], s[0:1], v100, s68, v[74:75]
	v_ashrrev_i32_e32 v53, 31, v52
	v_lshl_add_u64 v[74:75], v[74:75], 0, s[88:89]
	v_lshlrev_b64 v[102:103], 1, v[52:53]
	v_lshl_add_u64 v[52:53], v[74:75], 0, v[102:103]
	global_load_dwordx2 v[104:105], v[52:53], off
	global_load_dwordx2 v[150:151], v[52:53], off offset:16
	global_load_dwordx2 v[152:153], v[52:53], off offset:32
	global_load_dwordx2 v[154:155], v[52:53], off offset:48
	global_load_dwordx2 v[156:157], v[52:53], off offset:64
	global_load_dwordx2 v[158:159], v[52:53], off offset:80
	global_load_dwordx2 v[160:161], v[52:53], off offset:96
	global_load_dwordx2 v[162:163], v[52:53], off offset:112
	v_mfma_f32_32x32x16_bf16 v[32:47], v[76:79], v[66:69], v[32:47]
	v_cvt_pk_bf16_f32 v52, v101, v106
	v_cvt_pk_bf16_f32 v53, v107, v108
	v_mov_b32_e32 v106, v129
	v_mov_b32_e32 v108, v129
	v_mov_b32_e32 v107, v129
	v_mov_b32_e32 v109, v129
	v_dot2c_f32_bf16_e32 v106, 0x3f803f80, v66
	v_dot2c_f32_bf16_e32 v108, 0x3f803f80, v67
	v_dot2c_f32_bf16_e32 v107, 0x3f803f80, v68
	v_dot2c_f32_bf16_e32 v109, 0x3f803f80, v69
	v_dot2c_f32_bf16_e32 v106, 0x3f803f80, v58
	v_dot2c_f32_bf16_e32 v108, 0x3f803f80, v59
	v_dot2c_f32_bf16_e32 v107, 0x3f803f80, v60
	v_dot2c_f32_bf16_e32 v109, 0x3f803f80, v61
	v_dot2c_f32_bf16_e32 v106, 0x3f803f80, v54
	v_dot2c_f32_bf16_e32 v108, 0x3f803f80, v55
	v_dot2c_f32_bf16_e32 v107, 0x3f803f80, v56
	v_dot2c_f32_bf16_e32 v109, 0x3f803f80, v57
	v_mfma_f32_32x32x16_bf16 v[32:47], v[84:87], v[58:61], v[32:47]
	v_dot2c_f32_bf16_e32 v106, 0x3f803f80, v50
	v_dot2c_f32_bf16_e32 v108, 0x3f803f80, v51
	v_dot2c_f32_bf16_e32 v107, 0x3f803f80, v52
	v_dot2c_f32_bf16_e32 v109, 0x3f803f80, v53
	ds_bpermute_b32 v48, v192, v48
	v_ashrrev_i32_e32 v101, 31, v100
	s_add_i32 s20, s20, s28
	v_pk_add_f32 v[76:77], v[106:107], v[108:109]
	v_mfma_f32_32x32x16_bf16 v[32:47], v[92:95], v[54:57], v[32:47]
	v_add_f32_e32 v76, v76, v77
	ds_bpermute_b32 v77, v191, v76
	s_cmpk_gt_i32 s20, 0xff
	s_waitcnt lgkmcnt(0)
	v_add_f32_e32 v76, v76, v77
	v_add_f32_e32 v48, v76, v48
	v_div_scale_f32 v76, s[0:1], v48, v48, 1.0
	v_rcp_f32_e32 v77, v76
	v_mfma_f32_32x32x16_bf16 v[32:47], v[96:99], v[50:53], v[32:47]
	v_fma_f32 v78, -v76, v77, 1.0
	v_fmac_f32_e32 v77, v78, v77
	v_div_scale_f32 v78, vcc, 1.0, v48, 1.0
	v_mul_f32_e32 v79, v78, v77
	v_fma_f32 v84, -v76, v79, v78
	v_fmac_f32_e32 v79, v84, v77
	v_fma_f32 v76, -v76, v79, v78
	v_div_fmas_f32 v76, v76, v77, v79
	v_div_fixup_f32 v48, v76, v48, 1.0
	s_nop 2
	v_pk_mul_f32 v[32:33], v[32:33], v[48:49] op_sel_hi:[1,0]
	v_lshlrev_b64 v[76:77], 12, v[100:101]
	v_lshl_add_u64 v[76:77], s[4:5], 0, v[76:77]
	v_mfma_f32_32x32x16_bf16 v[16:31], v[80:83], v[66:69], v[16:31]
	v_mul_f32_e64 v36, v36, v48
	v_mul_f32_e64 v37, v37, v48
	v_mul_f32_e64 v38, v38, v48
	v_mul_f32_e64 v39, v39, v48
	s_waitcnt vmcnt(7)
	v_lshlrev_b32_e32 v78, 16, v104
	v_and_b32_e32 v79, 0xffff0000, v104
	v_pk_mul_f32 v[32:33], v[32:33], v[78:79]
	v_mfma_f32_32x32x16_bf16 v[16:31], v[88:91], v[58:61], v[16:31]
	v_cvt_pk_bf16_f32 v78, v32, v33
	v_mul_f32_e64 v32, v34, v48
	v_mul_f32_e64 v33, v35, v48
	v_lshlrev_b32_e32 v34, 16, v105
	v_and_b32_e32 v35, 0xffff0000, v105
	v_pk_mul_f32 v[32:33], v[32:33], v[34:35]
	v_add_u32_e32 v34, 0x208, v49
	v_cvt_pk_bf16_f32 v79, v32, v33
	v_lshl_add_u64 v[32:33], v[76:77], 0, v[102:103]
	v_ashrrev_i32_e32 v35, 31, v34
	global_store_dwordx2 v[32:33], v[78:79], off
	v_lshl_add_u64 v[34:35], v[34:35], 1, v[74:75]
	v_add_u32_e32 v76, 0x210, v49
	v_ashrrev_i32_e32 v77, 31, v76
	v_lshl_add_u64 v[76:77], v[76:77], 1, v[74:75]
	v_mfma_f32_32x32x16_bf16 v[16:31], v[70:73], v[54:57], v[16:31]
	s_waitcnt vmcnt(7)
; DI float bflo(unsigned u) { return __uint_as_float(u << 16); }
; DI float bfhi(unsigned u) { return __uint_as_float(u & 0xffff0000u); }
; #define RELANE(x) int x = (int)__builtin_amdgcn_mbcnt_hi(~0u, __builtin_amdgcn_mbcnt_lo(~0u, 0u)); asm volatile("" : "+v"(x));
; DI void store_y64(const f32x16 (&o)[2], float linv, bf16_t* Y, const bf16_t* proj, int token, int ycol, int hi) {
; #pragma unroll
;     for (int d0 = 0; d0 < 2; ++d0)
; #pragma unroll
;         for (int g = 0; g < 4; ++g) {
;             const int col = ycol + 32 * d0 + 8 * g + 4 * hi;
;             const u32x2 gv = *(const u32x2*)(proj + (size_t)token * LDP + C_SILU + col);
;             u32x2 w;
;             w.x = cvt_pk(o[d0][4 * g + 0] * linv * bflo(gv.x), o[d0][4 * g + 1] * linv * bfhi(gv.x));
;             w.y = cvt_pk(o[d0][4 * g + 2] * linv * bflo(gv.y), o[d0][4 * g + 3] * linv * bfhi(gv.y));
;             *(u32x2*)(Y + (size_t)token * DM + col) = w;
;         }
; __global__ void __launch_bounds__(512) mega(Params P) {
;     ...
;                 { RELANE(l2) int u2 = u; asm volatile("" : "+s"(u2)); const int h2 = u2 >> 5, q02 = (u2 & 31) * 256 + wid * 32;
;                   store_y64(o, 1.0f / lsum, Yb, proj, q02 + (l2 & 31), 512 + h2 * 64, l2 >> 5); }
	v_lshlrev_b32_e32 v66, 16, v150
	v_and_b32_e32 v67, 0xffff0000, v150
	v_lshlrev_b32_e32 v34, 16, v151
	v_and_b32_e32 v35, 0xffff0000, v151
	v_pk_mul_f32 v[36:37], v[36:37], v[66:67]
	v_pk_mul_f32 v[34:35], v[38:39], v[34:35]
	v_cvt_pk_bf16_f32 v36, v36, v37
	v_cvt_pk_bf16_f32 v37, v34, v35
	global_store_dwordx2 v[32:33], v[36:37], off offset:16
	v_pk_mul_f32 v[38:39], v[40:41], v[48:49] op_sel_hi:[1,0]
	v_pk_mul_f32 v[40:41], v[42:43], v[48:49] op_sel_hi:[1,0]
	v_add_u32_e32 v36, 0x218, v49
	v_ashrrev_i32_e32 v37, 31, v36
	v_lshl_add_u64 v[36:37], v[36:37], 1, v[74:75]
	v_mfma_f32_32x32x16_bf16 v[16:31], v[62:65], v[50:53], v[16:31]
	s_waitcnt vmcnt(7)
	v_lshlrev_b32_e32 v42, 16, v152
	v_and_b32_e32 v43, 0xffff0000, v152
	v_lshlrev_b32_e32 v34, 16, v153
	v_and_b32_e32 v35, 0xffff0000, v153
	v_pk_mul_f32 v[38:39], v[38:39], v[42:43]
	v_pk_mul_f32 v[34:35], v[40:41], v[34:35]
	v_cvt_pk_bf16_f32 v38, v38, v39
	v_cvt_pk_bf16_f32 v39, v34, v35
	global_store_dwordx2 v[32:33], v[38:39], off offset:32
	v_pk_mul_f32 v[38:39], v[44:45], v[48:49] op_sel_hi:[1,0]
	v_pk_mul_f32 v[40:41], v[46:47], v[48:49] op_sel_hi:[1,0]
	v_add_u32_e32 v36, 0x220, v49
	v_ashrrev_i32_e32 v37, 31, v36
	v_lshl_add_u64 v[36:37], v[36:37], 1, v[74:75]
	v_pk_mul_f32 v[16:17], v[16:17], v[48:49] op_sel_hi:[1,0]
	v_pk_mul_f32 v[18:19], v[18:19], v[48:49] op_sel_hi:[1,0]
	v_pk_mul_f32 v[20:21], v[20:21], v[48:49] op_sel_hi:[1,0]
	v_pk_mul_f32 v[22:23], v[22:23], v[48:49] op_sel_hi:[1,0]
	s_waitcnt vmcnt(7)
	v_lshlrev_b32_e32 v42, 16, v154
	v_and_b32_e32 v43, 0xffff0000, v154
	v_lshlrev_b32_e32 v34, 16, v155
	v_and_b32_e32 v35, 0xffff0000, v155
	v_pk_mul_f32 v[38:39], v[38:39], v[42:43]
	v_pk_mul_f32 v[34:35], v[40:41], v[34:35]
	v_cvt_pk_bf16_f32 v38, v38, v39
	v_cvt_pk_bf16_f32 v39, v34, v35
	global_store_dwordx2 v[32:33], v[38:39], off offset:48
	v_add_u32_e32 v36, 0x228, v49
	v_ashrrev_i32_e32 v37, 31, v36
	v_lshl_add_u64 v[36:37], v[36:37], 1, v[74:75]
	s_waitcnt vmcnt(7)
	v_lshlrev_b32_e32 v38, 16, v156
	v_and_b32_e32 v39, 0xffff0000, v156
	v_lshlrev_b32_e32 v34, 16, v157
	v_and_b32_e32 v35, 0xffff0000, v157
	v_pk_mul_f32 v[16:17], v[16:17], v[38:39]
	v_pk_mul_f32 v[18:19], v[18:19], v[34:35]
	v_cvt_pk_bf16_f32 v16, v16, v17
	v_cvt_pk_bf16_f32 v17, v18, v19
	global_store_dwordx2 v[32:33], v[16:17], off offset:64
	v_add_u32_e32 v18, 0x230, v49
	v_ashrrev_i32_e32 v19, 31, v18
	v_lshl_add_u64 v[18:19], v[18:19], 1, v[74:75]
	s_waitcnt vmcnt(7)
	v_lshlrev_b32_e32 v34, 16, v158
	v_and_b32_e32 v35, 0xffff0000, v158
	v_lshlrev_b32_e32 v16, 16, v159
	v_and_b32_e32 v17, 0xffff0000, v159
	v_pk_mul_f32 v[20:21], v[20:21], v[34:35]
	v_pk_mul_f32 v[16:17], v[22:23], v[16:17]
	v_cvt_pk_bf16_f32 v20, v20, v21
	v_cvt_pk_bf16_f32 v21, v16, v17
	global_store_dwordx2 v[32:33], v[20:21], off offset:80
	v_pk_mul_f32 v[20:21], v[24:25], v[48:49] op_sel_hi:[1,0]
	v_pk_mul_f32 v[22:23], v[26:27], v[48:49] op_sel_hi:[1,0]
	v_add_u32_e32 v18, 0x238, v49
	v_ashrrev_i32_e32 v19, 31, v18
	v_lshl_add_u64 v[18:19], v[18:19], 1, v[74:75]
	s_waitcnt vmcnt(7)
	v_lshlrev_b32_e32 v24, 16, v160
	v_and_b32_e32 v25, 0xffff0000, v160
	v_lshlrev_b32_e32 v16, 16, v161
	v_and_b32_e32 v17, 0xffff0000, v161
	v_pk_mul_f32 v[20:21], v[20:21], v[24:25]
	v_pk_mul_f32 v[16:17], v[22:23], v[16:17]
	v_cvt_pk_bf16_f32 v20, v20, v21
	v_cvt_pk_bf16_f32 v21, v16, v17
	global_store_dwordx2 v[32:33], v[20:21], off offset:96
	v_pk_mul_f32 v[18:19], v[28:29], v[48:49] op_sel_hi:[1,0]
	v_pk_mul_f32 v[20:21], v[30:31], v[48:49] op_sel_hi:[1,0]
	s_waitcnt vmcnt(7)
	v_lshlrev_b32_e32 v22, 16, v162
	v_and_b32_e32 v23, 0xffff0000, v162
	v_lshlrev_b32_e32 v16, 16, v163
	v_and_b32_e32 v17, 0xffff0000, v163
	v_pk_mul_f32 v[18:19], v[18:19], v[22:23]
	v_pk_mul_f32 v[16:17], v[20:21], v[16:17]
	v_cvt_pk_bf16_f32 v18, v18, v19
	v_cvt_pk_bf16_f32 v19, v16, v17
	global_store_dwordx2 v[32:33], v[18:19], off offset:112
	s_cbranch_scc0 .LBB0_382

.LBB0_635:
	s_or_b64 exec, exec, s[8:9]
	global_load_dwordx4 v[162:165], v[184:185], off
	s_add_i32 s8, s10, -1
	s_and_b32 s11, s8, 1
	s_mul_i32 s8, s11, 0x3400
	v_add_u32_e32 v174, s8, v196
	ds_read_b128 v[80:83], v174
	ds_read_b128 v[204:207], v174 offset:32
	ds_read_b128 v[208:211], v174 offset:6656
	ds_read_b128 v[214:217], v174 offset:6688
	s_xor_b32 s8, s11, 1
	s_mulk_i32 s8, 0x3000
	v_add_u32_e32 v176, s8, v198
	s_waitcnt lgkmcnt(3)
	v_mfma_f32_32x32x16_bf16 v[96:111], v[80:83], v[142:145], v[48:63]
	ds_read_b128 v[222:225], v174 offset:64
	ds_read_b64_tr_b16 v[226:227], v176 offset:26624
	ds_read_b64_tr_b16 v[228:229], v176 offset:28160
	s_waitcnt lgkmcnt(4)
	v_mfma_f32_32x32x16_bf16 v[80:95], v[208:211], v[142:145], v[48:63]
	ds_read_b128 v[208:211], v174 offset:6720
	ds_read_b64_tr_b16 v[230:231], v176 offset:26688
	ds_read_b64_tr_b16 v[232:233], v176 offset:28224
	v_mfma_f32_32x32x16_bf16 v[96:111], v[204:207], v[138:141], v[96:111]
	ds_read_b128 v[204:207], v174 offset:96
	ds_read_b64_tr_b16 v[234:235], v176 offset:29696
	ds_read_b64_tr_b16 v[236:237], v176 offset:31232
	s_waitcnt lgkmcnt(9)
	v_mfma_f32_32x32x16_bf16 v[80:95], v[214:217], v[138:141], v[80:95]
	ds_read_b128 v[214:217], v174 offset:6752
	ds_read_b64_tr_b16 v[238:239], v176 offset:29760
	ds_read_b64_tr_b16 v[240:241], v176 offset:31296
	s_waitcnt lgkmcnt(11)
	v_mfma_f32_32x32x16_bf16 v[96:111], v[222:225], v[134:137], v[96:111]
	ds_read_b128 v[222:225], v174 offset:128
	ds_read_b64_tr_b16 v[242:243], v176 offset:32768
	ds_read_b64_tr_b16 v[244:245], v176 offset:34304
	s_waitcnt lgkmcnt(11)
	v_mfma_f32_32x32x16_bf16 v[80:95], v[208:211], v[134:137], v[80:95]
	ds_read_b128 v[208:211], v174 offset:6784
	ds_read_b64_tr_b16 v[246:247], v176 offset:32832
	ds_read_b64_tr_b16 v[248:249], v176 offset:34368
	s_waitcnt lgkmcnt(11)
	v_mfma_f32_32x32x16_bf16 v[96:111], v[204:207], v[130:133], v[96:111]
	ds_read_b128 v[204:207], v174 offset:160
	ds_read_b64_tr_b16 v[186:187], v176 offset:35840
	ds_read_b64_tr_b16 v[188:189], v176 offset:37376
	s_waitcnt lgkmcnt(11)
	v_mfma_f32_32x32x16_bf16 v[80:95], v[214:217], v[130:133], v[80:95]
	ds_read_b128 v[214:217], v174 offset:6816
	ds_read_b64_tr_b16 v[174:175], v176 offset:35904
	ds_read_b64_tr_b16 v[176:177], v176 offset:37440
	s_waitcnt lgkmcnt(11)
	v_mfma_f32_32x32x16_bf16 v[96:111], v[222:225], v[120:123], v[96:111]
	s_waitcnt lgkmcnt(8)
	v_mfma_f32_32x32x16_bf16 v[80:95], v[208:211], v[120:123], v[80:95]
	s_waitcnt lgkmcnt(5)
	v_mfma_f32_32x32x16_bf16 v[96:111], v[204:207], v[116:119], v[96:111]
	s_waitcnt lgkmcnt(2)
	v_mfma_f32_32x32x16_bf16 v[80:95], v[214:217], v[116:119], v[80:95]
	v_mfma_f32_32x32x16_bf16 v[32:47], v[226:229], v[158:161], v[32:47]
	v_mfma_f32_32x32x16_bf16 v[16:31], v[230:233], v[158:161], v[16:31]
	v_mfma_f32_32x32x16_bf16 v[32:47], v[234:237], v[154:157], v[32:47]
	v_mfma_f32_32x32x16_bf16 v[16:31], v[238:241], v[154:157], v[16:31]
	v_mfma_f32_32x32x16_bf16 v[32:47], v[242:245], v[150:153], v[32:47]
	v_mfma_f32_32x32x16_bf16 v[16:31], v[246:249], v[150:153], v[16:31]
	v_mfma_f32_32x32x16_bf16 v[32:47], v[186:189], v[146:149], v[32:47]
	s_waitcnt lgkmcnt(0)
	v_mfma_f32_32x32x16_bf16 v[16:31], v[174:177], v[146:149], v[16:31]
	s_bitcmp1_b32 s10, 0
	s_cselect_b32 s8, 0x3400, 0
	s_add_i32 s16, s8, 0
	v_add_u32_e32 v174, s16, v194
	s_waitcnt vmcnt(1)
	ds_write_b128 v174, v[166:169]
	s_and_saveexec_b64 s[8:9], s[0:1]
	v_add_u32_e32 v166, s16, v195
	ds_write_b128 v166, v[124:127]
	s_or_b64 exec, exec, s[8:9]
	s_mulk_i32 s11, 0x3000
	v_add_u32_e32 v175, s11, v197
	s_waitcnt vmcnt(0)
	ds_write_b128 v175, v[162:165] offset:26624
	v_mfma_f32_32x32x16_bf16 v[64:79], v[112:115], v[158:161], v[64:79]
	v_exp_f32_e32 v166, v96
	v_exp_f32_e32 v167, v97
	v_exp_f32_e32 v98, v98
	v_exp_f32_e32 v99, v99
	v_exp_f32_e32 v168, v100
	v_exp_f32_e32 v169, v101
	v_exp_f32_e32 v174, v102
	v_mfma_f32_32x32x16_bf16 v[64:79], v[112:115], v[154:157], v[64:79]
	v_exp_f32_e32 v175, v103
	v_exp_f32_e32 v104, v104
	v_exp_f32_e32 v176, v105
	v_exp_f32_e32 v105, v106
	v_exp_f32_e32 v177, v107
	v_exp_f32_e32 v106, v108
	v_exp_f32_e32 v108, v109
	v_mfma_f32_32x32x16_bf16 v[64:79], v[112:115], v[150:153], v[64:79]
	v_exp_f32_e32 v107, v110
	v_exp_f32_e32 v109, v111
	v_exp_f32_e32 v80, v80
	v_exp_f32_e32 v81, v81
	v_exp_f32_e32 v82, v82
	v_exp_f32_e32 v83, v83
	v_exp_f32_e32 v84, v84
	v_mfma_f32_32x32x16_bf16 v[64:79], v[112:115], v[146:149], v[64:79]
	v_exp_f32_e32 v85, v85
	v_exp_f32_e32 v86, v86
	v_exp_f32_e32 v87, v87
	v_exp_f32_e32 v88, v88
	v_exp_f32_e32 v89, v89
	v_exp_f32_e32 v90, v90
	v_exp_f32_e32 v91, v91
	v_exp_f32_e32 v92, v92
	v_exp_f32_e32 v93, v93
	v_exp_f32_e32 v94, v94
	v_exp_f32_e32 v95, v95
	s_add_i32 s10, s10, 1
	s_mov_b64 s[8:9], 0x2000
	v_cvt_pk_bf16_f32 v97, v90, v91
	v_cvt_pk_bf16_f32 v96, v88, v89
	v_cvt_pk_bf16_f32 v103, v86, v87
	v_cvt_pk_bf16_f32 v102, v84, v85
	v_cvt_pk_bf16_f32 v101, v82, v83
	v_cvt_pk_bf16_f32 v100, v80, v81
	v_cvt_pk_bf16_f32 v107, v107, v109
	v_cvt_pk_bf16_f32 v106, v106, v108
	v_cvt_pk_bf16_f32 v105, v105, v177
	v_cvt_pk_bf16_f32 v104, v104, v176
	v_cvt_pk_bf16_f32 v111, v174, v175
	v_cvt_pk_bf16_f32 v110, v168, v169
	v_cvt_pk_bf16_f32 v109, v98, v99
	v_cvt_pk_bf16_f32 v108, v166, v167
	v_cvt_pk_bf16_f32 v98, v92, v93
	v_cvt_pk_bf16_f32 v99, v94, v95
	v_lshl_add_u64 v[184:185], v[184:185], 0, s[8:9]
	v_lshl_add_u64 v[190:191], v[190:191], 0, s[92:93]
	s_cmpk_eq_i32 s10, 0x80
	v_lshl_add_u64 v[192:193], v[192:193], 0, s[92:93]
	s_waitcnt lgkmcnt(0)
	s_barrier
	s_cbranch_scc1 .LBB0_639
	v_mov_b32_e32 v158, v108
	v_mov_b32_e32 v159, v109
	v_mov_b32_e32 v160, v110
	v_mov_b32_e32 v161, v111
	v_mov_b32_e32 v154, v104
	v_mov_b32_e32 v155, v105
	v_mov_b32_e32 v156, v106
	v_mov_b32_e32 v157, v107
	v_mov_b32_e32 v150, v100
	v_mov_b32_e32 v151, v101
	v_mov_b32_e32 v152, v102
	v_mov_b32_e32 v153, v103
	v_mov_b32_e32 v146, v96
	v_mov_b32_e32 v147, v97
	v_mov_b32_e32 v148, v98
	v_mov_b32_e32 v149, v99
	global_load_dwordx4 v[166:169], v[190:191], off
	s_and_saveexec_b64 s[8:9], s[0:1]
	s_cbranch_execnz .LBB0_634
	s_branch .LBB0_635
